# v43 + FoX/MLA in-loop tiles: K-fragment LDS reads hoisted to the top of the tile body so their latency hides under the next-tile address arithmetic and loads
# baseline (speedup 1.0000x reference)
; #define LAS __attribute__((address_space(3)))
; template <int TY> __device__ __forceinline__ void attn_unit(LAS unsigned char* lds, const AttnArgs& a, int b, int h, int qt, int wave_s) {
;     ...
;         { const int Jn = J + 2 <= J1 ? J + 2 : J1; if (hf == 0) ATT_LOAD(A, Jn); else ATT_LOAD(B, Jn); }
;         const bool skip = (64 * J > ewhi) || (TY == 0 && 64 * J + 63 + 127 < ewlo);
;         if (!skip) {
;         int lim[2]; f32x4 cinit[2];
; #pragma unroll
;         for (int qb = 0; qb < 2; ++qb) {
;             lim[qb] = eq[qb] - 64 * J - 4 * fq;
;             const float c0 = TY == 0 ? -(mrun[qb] + slope2 * (float)lim[qb]) : -mrun[qb];
;             cinit[qb] = (f32x4){c0, c0, c0, c0};
;         }
;         f32x4 s[2][4];
;         bf16x8 kfr[4][NDS];
; #pragma unroll
;         for (int kb = 0; kb < 4; ++kb)
; #pragma unroll
;             for (int ds = 0; ds < NDS; ++ds) kfr[kb][ds] = *(const LAS bf16x8*)(sb + koff + (kb * NDS + ds) * 1024);
; #pragma unroll
;         for (int kb = 0; kb < 4; ++kb) {
; #pragma unroll
;             for (int ds = 0; ds < NDS; ++ds) {
;                 s[0][kb] = __builtin_amdgcn_mfma_f32_16x16x32_bf16(kfr[kb][ds], qf[0][ds], ds == 0 ? cinit[0] : s[0][kb], 0, 0, 0);
;                 s[1][kb] = __builtin_amdgcn_mfma_f32_16x16x32_bf16(kfr[kb][ds], qf[1][ds], ds == 0 ? cinit[1] : s[1][kb], 0, 0, 0);
;             }
;         }
.LBB0_700:
	s_add_i32 s22, s20, -3
	s_cmp_le_u32 s22, s18
	s_cselect_b64 s[6:7], -1, 0
	s_and_b64 vcc, exec, s[6:7]
	s_cbranch_vccz .LBB0_714
	ds_read_b128 v[10:13], v211
	ds_read_b128 v[106:109], v211 offset:1024
	ds_read_b128 v[114:117], v211 offset:2048
	ds_read_b128 v[118:121], v211 offset:3072
	ds_read_b128 v[122:125], v211 offset:4096
	ds_read_b128 v[126:129], v211 offset:5120
	ds_read_b128 v[134:137], v211 offset:6144
	ds_read_b128 v[138:141], v211 offset:7168
	ds_read_b128 v[142:145], v211 offset:8192
	ds_read_b128 v[150:153], v211 offset:9216
	ds_read_b128 v[158:161], v211 offset:10240
	ds_read_b128 v[164:167], v211 offset:11264
	s_add_i32 s8, s20, -1
	s_min_i32 s8, s8, s18
	s_lshl_b32 s8, s8, 6
	v_add_u32_e32 v232, s8, v207
	v_max_i32_e32 v234, 48, v232
	v_add_u32_e32 v233, s17, v232
	v_add_u32_e32 v234, s11, v234
	v_cmp_lt_i32_e32 vcc, 63, v232
	s_nop 1
	v_cndmask_b32_e32 v232, v234, v233, vcc
	v_ashrrev_i32_e32 v233, 31, v232
	v_lshlrev_b64 v[232:233], 11, v[232:233]
	v_lshl_add_u64 v[232:233], v[192:193], 0, v[232:233]
	global_load_dwordx4 v[78:81], v[232:233], off
	global_load_dwordx4 v[82:85], v[232:233], off offset:128
	v_add_u32_e32 v232, s8, v18
	v_ashrrev_i32_e32 v233, 31, v232
	v_lshlrev_b64 v[232:233], 6, v[232:233]
	v_lshl_add_u64 v[232:233], v[20:21], 0, v[232:233]
	global_load_dwordx4 v[86:89], v[232:233], off
	s_add_i32 s8, s21, 0xffffff81
	s_cmp_gt_i32 s8, s19
	s_cbranch_scc1 .LBB0_709
	v_xor_b32_e32 v14, 0x80000000, v195
	v_xor_b32_e32 v110, 0x80000000, v194
	v_mov_b32_e32 v15, v14
	v_mov_b32_e32 v16, v14
	v_mov_b32_e32 v17, v14
	v_mov_b32_e32 v111, v110
	v_mov_b32_e32 v112, v110
	v_mov_b32_e32 v113, v110
	s_waitcnt lgkmcnt(11)
	v_mfma_f32_16x16x32_bf16 v[130:133], v[10:13], v[38:41], v[14:17]
	s_sub_i32 s8, s21, 64
	s_cmp_gt_i32 s8, s10
	s_mov_b64 s[8:9], -1
	v_mfma_f32_16x16x32_bf16 v[10:13], v[10:13], v[46:49], v[110:113]
	s_waitcnt lgkmcnt(10)
	v_mfma_f32_16x16x32_bf16 v[130:133], v[106:109], v[42:45], v[130:133]
	v_mfma_f32_16x16x32_bf16 v[10:13], v[106:109], v[50:53], v[10:13]
	s_waitcnt lgkmcnt(9)
	v_mfma_f32_16x16x32_bf16 v[130:133], v[114:117], v[58:61], v[130:133]
	v_mfma_f32_16x16x32_bf16 v[10:13], v[114:117], v[62:65], v[10:13]
	s_waitcnt lgkmcnt(8)
	v_mfma_f32_16x16x32_bf16 v[106:109], v[118:121], v[38:41], v[14:17]
	v_mfma_f32_16x16x32_bf16 v[114:117], v[118:121], v[46:49], v[110:113]
	s_waitcnt lgkmcnt(7)
	v_mfma_f32_16x16x32_bf16 v[106:109], v[122:125], v[42:45], v[106:109]
	v_mfma_f32_16x16x32_bf16 v[114:117], v[122:125], v[50:53], v[114:117]
	s_waitcnt lgkmcnt(6)
	v_mfma_f32_16x16x32_bf16 v[146:149], v[126:129], v[58:61], v[106:109]
	v_mfma_f32_16x16x32_bf16 v[106:109], v[126:129], v[62:65], v[114:117]
	s_waitcnt lgkmcnt(5)
	v_mfma_f32_16x16x32_bf16 v[114:117], v[134:137], v[38:41], v[14:17]
	v_mfma_f32_16x16x32_bf16 v[118:121], v[134:137], v[46:49], v[110:113]
	s_waitcnt lgkmcnt(2)
	v_mfma_f32_16x16x32_bf16 v[110:113], v[150:153], v[46:49], v[110:113]
	v_mfma_f32_16x16x32_bf16 v[114:117], v[138:141], v[42:45], v[114:117]
	v_mfma_f32_16x16x32_bf16 v[118:121], v[138:141], v[50:53], v[118:121]
	v_mfma_f32_16x16x32_bf16 v[14:17], v[150:153], v[38:41], v[14:17]
	s_waitcnt lgkmcnt(1)
	v_mfma_f32_16x16x32_bf16 v[110:113], v[158:161], v[50:53], v[110:113]
	v_mfma_f32_16x16x32_bf16 v[154:157], v[142:145], v[58:61], v[114:117]
	v_mfma_f32_16x16x32_bf16 v[126:129], v[142:145], v[62:65], v[118:121]
	v_mfma_f32_16x16x32_bf16 v[14:17], v[158:161], v[42:45], v[14:17]
	s_waitcnt lgkmcnt(0)
	v_mfma_f32_16x16x32_bf16 v[134:137], v[164:167], v[62:65], v[110:113]
	ds_read_b64_tr_b16 v[122:123], v212 offset:12288
	s_nop 1
	ds_read_b64_tr_b16 v[110:111], v212 offset:12320
	ds_read_b64_tr_b16 v[124:125], v212 offset:14848
	ds_read_b64_tr_b16 v[118:119], v212 offset:17408
	ds_read_b64_tr_b16 v[120:121], v212 offset:19968
	ds_read_b64_tr_b16 v[112:113], v212 offset:14880
	ds_read_b64_tr_b16 v[114:115], v212 offset:17440
	ds_read_b64_tr_b16 v[116:117], v212 offset:20000
	ds_read_b64_tr_b16 v[142:143], v212 offset:12352
	ds_read_b64_tr_b16 v[144:145], v212 offset:14912
	ds_read_b64_tr_b16 v[138:139], v212 offset:17472
	ds_read_b64_tr_b16 v[140:141], v212 offset:20032
	ds_read_b64_tr_b16 v[150:151], v212 offset:12384
	ds_read_b64_tr_b16 v[152:153], v212 offset:14944
	ds_read_b64_tr_b16 v[158:159], v212 offset:17504
	ds_read_b64_tr_b16 v[160:161], v212 offset:20064
	v_mfma_f32_16x16x32_bf16 v[14:17], v[164:167], v[58:61], v[14:17]
	s_cbranch_scc1 .LBB0_704
	s_mov_b64 s[8:9], 0

; #define LAS __attribute__((address_space(3)))
; template <int TY> __device__ __forceinline__ void attn_unit(LAS unsigned char* lds, const AttnArgs& a, int b, int h, int qt, int wave_s) {
;     ...
;         { const int Jn = J + 2 <= J1 ? J + 2 : J1; if (hf == 0) ATT_LOAD(A, Jn); else ATT_LOAD(B, Jn); }
;         const bool skip = (64 * J > ewhi) || (TY == 0 && 64 * J + 63 + 127 < ewlo);
;         if (!skip) {
;         int lim[2]; f32x4 cinit[2];
; #pragma unroll
;         for (int qb = 0; qb < 2; ++qb) {
;             lim[qb] = eq[qb] - 64 * J - 4 * fq;
;             const float c0 = TY == 0 ? -(mrun[qb] + slope2 * (float)lim[qb]) : -mrun[qb];
;             cinit[qb] = (f32x4){c0, c0, c0, c0};
;         }
;         f32x4 s[2][4];
;         bf16x8 kfr[4][NDS];
; #pragma unroll
;         for (int kb = 0; kb < 4; ++kb)
; #pragma unroll
;             for (int ds = 0; ds < NDS; ++ds) kfr[kb][ds] = *(const LAS bf16x8*)(sb + koff + (kb * NDS + ds) * 1024);
; #pragma unroll
;         for (int kb = 0; kb < 4; ++kb) {
; #pragma unroll
;             for (int ds = 0; ds < NDS; ++ds) {
;                 s[0][kb] = __builtin_amdgcn_mfma_f32_16x16x32_bf16(kfr[kb][ds], qf[0][ds], ds == 0 ? cinit[0] : s[0][kb], 0, 0, 0);
;                 s[1][kb] = __builtin_amdgcn_mfma_f32_16x16x32_bf16(kfr[kb][ds], qf[1][ds], ds == 0 ? cinit[1] : s[1][kb], 0, 0, 0);
;             }
;         }
;         bf16x8 vf[4][2];
; #pragma unroll
;         for (int db = 0; db < 4; ++db)
; #pragma unroll
;             for (int G = 0; G < 2; ++G) {
;                 LAS unsigned char* vp = sb + voff + (32 * G * VSTR + 16 * db) * 2;
;                 const v4i16_t lo = __builtin_amdgcn_ds_read_tr16_b64_v4i16((LAS v4i16_t*)vp), hi = __builtin_amdgcn_ds_read_tr16_b64_v4i16((LAS v4i16_t*)(vp + 16 * VSTR * 2));
;                 vf[db][G] = (bf16x8){lo[0], lo[1], lo[2], lo[3], hi[0], hi[1], hi[2], hi[3]};
;             }
.LBB0_714:
	s_andn2_b64 vcc, exec, s[6:7]
	s_cbranch_vccnz .LBB0_699
	s_cmp_ge_u32 s22, s18
	s_cbranch_scc1 .LBB0_699
	ds_read_b128 v[10:13], v211 offset:22784
	ds_read_b128 v[106:109], v211 offset:23808
	ds_read_b128 v[114:117], v211 offset:24832
	ds_read_b128 v[118:121], v211 offset:25856
	ds_read_b128 v[122:125], v211 offset:26880
	ds_read_b128 v[126:129], v211 offset:27904
	ds_read_b128 v[134:137], v211 offset:28928
	ds_read_b128 v[138:141], v211 offset:29952
	ds_read_b128 v[142:145], v211 offset:30976
	ds_read_b128 v[150:153], v211 offset:32000
	ds_read_b128 v[158:161], v211 offset:33024
	ds_read_b128 v[164:167], v211 offset:34048
	s_min_i32 s6, s20, s18
	s_lshl_b32 s6, s6, 6
	v_add_u32_e32 v232, s6, v207
	v_max_i32_e32 v234, 48, v232
	v_add_u32_e32 v233, s17, v232
	v_add_u32_e32 v234, s11, v234
	v_cmp_lt_i32_e32 vcc, 63, v232
	s_nop 1
	v_cndmask_b32_e32 v232, v234, v233, vcc
	v_ashrrev_i32_e32 v233, 31, v232
	v_lshlrev_b64 v[232:233], 11, v[232:233]
	v_lshl_add_u64 v[232:233], v[192:193], 0, v[232:233]
	global_load_dwordx4 v[66:69], v[232:233], off
	global_load_dwordx4 v[70:73], v[232:233], off offset:128
	v_add_u32_e32 v232, s6, v18
	v_ashrrev_i32_e32 v233, 31, v232
	v_lshlrev_b64 v[232:233], 6, v[232:233]
	v_lshl_add_u64 v[232:233], v[20:21], 0, v[232:233]
	global_load_dwordx4 v[74:77], v[232:233], off
	s_sub_i32 s6, s21, 63
	s_cmp_gt_i32 s6, s19
	s_cbranch_scc1 .LBB0_724
	v_xor_b32_e32 v14, 0x80000000, v195
	v_xor_b32_e32 v110, 0x80000000, v194
	v_mov_b32_e32 v15, v14
	v_mov_b32_e32 v16, v14
	v_mov_b32_e32 v17, v14
	v_mov_b32_e32 v111, v110
	v_mov_b32_e32 v112, v110
	v_mov_b32_e32 v113, v110
	s_waitcnt lgkmcnt(11)
	v_mfma_f32_16x16x32_bf16 v[130:133], v[10:13], v[38:41], v[14:17]
	s_cmp_gt_i32 s21, s10
	s_mov_b64 s[6:7], -1
	v_mfma_f32_16x16x32_bf16 v[10:13], v[10:13], v[46:49], v[110:113]
	s_waitcnt lgkmcnt(10)
	v_mfma_f32_16x16x32_bf16 v[130:133], v[106:109], v[42:45], v[130:133]
	v_mfma_f32_16x16x32_bf16 v[10:13], v[106:109], v[50:53], v[10:13]
	s_waitcnt lgkmcnt(9)
	v_mfma_f32_16x16x32_bf16 v[130:133], v[114:117], v[58:61], v[130:133]
	v_mfma_f32_16x16x32_bf16 v[10:13], v[114:117], v[62:65], v[10:13]
	s_waitcnt lgkmcnt(8)
	v_mfma_f32_16x16x32_bf16 v[106:109], v[118:121], v[38:41], v[14:17]
	v_mfma_f32_16x16x32_bf16 v[114:117], v[118:121], v[46:49], v[110:113]
	s_waitcnt lgkmcnt(7)
	v_mfma_f32_16x16x32_bf16 v[106:109], v[122:125], v[42:45], v[106:109]
	v_mfma_f32_16x16x32_bf16 v[114:117], v[122:125], v[50:53], v[114:117]
	s_waitcnt lgkmcnt(6)
	v_mfma_f32_16x16x32_bf16 v[146:149], v[126:129], v[58:61], v[106:109]
	v_mfma_f32_16x16x32_bf16 v[106:109], v[126:129], v[62:65], v[114:117]
	s_waitcnt lgkmcnt(5)
	v_mfma_f32_16x16x32_bf16 v[114:117], v[134:137], v[38:41], v[14:17]
	v_mfma_f32_16x16x32_bf16 v[118:121], v[134:137], v[46:49], v[110:113]
	s_waitcnt lgkmcnt(2)
	v_mfma_f32_16x16x32_bf16 v[110:113], v[150:153], v[46:49], v[110:113]
	v_mfma_f32_16x16x32_bf16 v[114:117], v[138:141], v[42:45], v[114:117]
	v_mfma_f32_16x16x32_bf16 v[118:121], v[138:141], v[50:53], v[118:121]
	v_mfma_f32_16x16x32_bf16 v[14:17], v[150:153], v[38:41], v[14:17]
	s_waitcnt lgkmcnt(1)
	v_mfma_f32_16x16x32_bf16 v[110:113], v[158:161], v[50:53], v[110:113]
	v_mfma_f32_16x16x32_bf16 v[154:157], v[142:145], v[58:61], v[114:117]
	v_mfma_f32_16x16x32_bf16 v[126:129], v[142:145], v[62:65], v[118:121]
	v_mfma_f32_16x16x32_bf16 v[14:17], v[158:161], v[42:45], v[14:17]
	s_waitcnt lgkmcnt(0)
	v_mfma_f32_16x16x32_bf16 v[134:137], v[164:167], v[62:65], v[110:113]
	ds_read_b64_tr_b16 v[122:123], v212 offset:35072
	s_nop 1
	ds_read_b64_tr_b16 v[110:111], v212 offset:35104
	ds_read_b64_tr_b16 v[124:125], v212 offset:37632
	ds_read_b64_tr_b16 v[118:119], v212 offset:40192
	ds_read_b64_tr_b16 v[120:121], v212 offset:42752
	ds_read_b64_tr_b16 v[112:113], v212 offset:37664
	ds_read_b64_tr_b16 v[114:115], v212 offset:40224
	ds_read_b64_tr_b16 v[116:117], v212 offset:42784
	ds_read_b64_tr_b16 v[142:143], v212 offset:35136
	ds_read_b64_tr_b16 v[144:145], v212 offset:37696
	ds_read_b64_tr_b16 v[138:139], v212 offset:40256
	ds_read_b64_tr_b16 v[140:141], v212 offset:42816
	ds_read_b64_tr_b16 v[150:151], v212 offset:35168
	ds_read_b64_tr_b16 v[152:153], v212 offset:37728
	ds_read_b64_tr_b16 v[158:159], v212 offset:40288
	ds_read_b64_tr_b16 v[160:161], v212 offset:42848
	v_mfma_f32_16x16x32_bf16 v[14:17], v[164:167], v[58:61], v[14:17]
	s_cbranch_scc1 .LBB0_719
	s_mov_b64 s[6:7], 0

; #define LAS __attribute__((address_space(3)))
; template <int TY> __device__ __forceinline__ void attn_unit(LAS unsigned char* lds, const AttnArgs& a, int b, int h, int qt, int wave_s) {
;     ...
;         { const int Jn = J + 2 <= J1 ? J + 2 : J1; if (hf == 0) ATT_LOAD(A, Jn); else ATT_LOAD(B, Jn); }
;         const bool skip = (64 * J > ewhi) || (TY == 0 && 64 * J + 63 + 127 < ewlo);
;         if (!skip) {
;         int lim[2]; f32x4 cinit[2];
; #pragma unroll
;         for (int qb = 0; qb < 2; ++qb) {
;             lim[qb] = eq[qb] - 64 * J - 4 * fq;
;             const float c0 = TY == 0 ? -(mrun[qb] + slope2 * (float)lim[qb]) : -mrun[qb];
;             cinit[qb] = (f32x4){c0, c0, c0, c0};
;         }
;         f32x4 s[2][4];
;         bf16x8 kfr[4][NDS];
; #pragma unroll
;         for (int kb = 0; kb < 4; ++kb)
; #pragma unroll
;             for (int ds = 0; ds < NDS; ++ds) kfr[kb][ds] = *(const LAS bf16x8*)(sb + koff + (kb * NDS + ds) * 1024);
; #pragma unroll
;         for (int kb = 0; kb < 4; ++kb) {
; #pragma unroll
;             for (int ds = 0; ds < NDS; ++ds) {
;                 s[0][kb] = __builtin_amdgcn_mfma_f32_16x16x32_bf16(kfr[kb][ds], qf[0][ds], ds == 0 ? cinit[0] : s[0][kb], 0, 0, 0);
;                 s[1][kb] = __builtin_amdgcn_mfma_f32_16x16x32_bf16(kfr[kb][ds], qf[1][ds], ds == 0 ? cinit[1] : s[1][kb], 0, 0, 0);
;             }
;         }
;         bf16x8 vf[4][2];
; #pragma unroll
;         for (int db = 0; db < 4; ++db)
; #pragma unroll
;             for (int G = 0; G < 2; ++G) {
;                 LAS unsigned char* vp = sb + voff + (32 * G * VSTR + 16 * db) * 2;
;                 const v4i16_t lo = __builtin_amdgcn_ds_read_tr16_b64_v4i16((LAS v4i16_t*)vp), hi = __builtin_amdgcn_ds_read_tr16_b64_v4i16((LAS v4i16_t*)(vp + 16 * VSTR * 2));
;                 vf[db][G] = (bf16x8){lo[0], lo[1], lo[2], lo[3], hi[0], hi[1], hi[2], hi[3]};
;             }
;         if (TY == 1) {
; #pragma unroll
;             for (int kb = 0; kb < 4; ++kb) {
;                 const f32x4 fk = *(const LAS f32x4*)(sb + KBYTES + VBYTES + (16 * kb + 4 * fq) * 4);
;                 s[0][kb] -= fk; s[1][kb] -= fk;
;             }
;         }
.LBB0_763:
	s_add_i32 s24, s22, -3
	s_cmp_le_u32 s24, s20
	s_cselect_b64 s[8:9], -1, 0
	s_and_b64 vcc, exec, s[8:9]
	s_cbranch_vccz .LBB0_777
	ds_read_b128 v[90:93], v186
	ds_read_b128 v[94:97], v186 offset:1024
	ds_read_b128 v[98:101], v186 offset:2048
	ds_read_b128 v[102:105], v186 offset:3072
	ds_read_b128 v[106:109], v186 offset:4096
	ds_read_b128 v[110:113], v186 offset:5120
	ds_read_b128 v[114:117], v186 offset:6144
	ds_read_b128 v[118:121], v186 offset:7168
	s_add_i32 s10, s22, -1
	s_min_i32 s10, s10, s20
	s_lshl_b32 s25, s10, 6
	v_add_u32_e32 v1, s25, v169
	v_max_i32_e32 v11, 48, v1
	v_add_u32_e32 v10, s19, v1
	v_add_u32_e32 v11, s18, v11
	v_cmp_lt_i32_e32 vcc, 63, v1
	s_nop 1
	v_cndmask_b32_e32 v1, v11, v10, vcc
	v_mad_i64_i32 v[10:11], s[10:11], v1, s40, v[162:163]
	v_mad_i64_i32 v[12:13], s[10:11], v1, s40, v[164:165]
	global_load_dwordx4 v[70:73], v[10:11], off
	global_load_dwordx4 v[74:77], v[12:13], off
	v_add_u32_e32 v10, s25, v144
	v_ashrrev_i32_e32 v11, 31, v10
	v_lshlrev_b64 v[10:11], 5, v[10:11]
	v_lshl_add_u64 v[10:11], s[6:7], 0, v[10:11]
	global_load_dword v189, v[10:11], off
	s_add_i32 s10, s23, 0xffffff81
	s_cmp_gt_i32 s10, s21
	s_cbranch_scc1 .LBB0_772
	v_xor_b32_e32 v10, 0x80000000, v167
	v_xor_b32_e32 v14, 0x80000000, v166
	v_mov_b32_e32 v11, v10
	v_mov_b32_e32 v12, v10
	v_mov_b32_e32 v13, v10
	v_mov_b32_e32 v15, v14
	v_mov_b32_e32 v16, v14
	v_mov_b32_e32 v17, v14
	s_waitcnt lgkmcnt(7)
	v_mfma_f32_16x16x32_bf16 v[122:125], v[90:93], v[38:41], v[10:13]
	s_sub_i32 s10, s23, 64
	s_cmp_gt_i32 s10, s17
	s_mov_b64 s[10:11], -1
	v_mfma_f32_16x16x32_bf16 v[90:93], v[90:93], v[46:49], v[14:17]
	s_waitcnt lgkmcnt(6)
	v_mfma_f32_16x16x32_bf16 v[126:129], v[94:97], v[42:45], v[122:125]
	v_mfma_f32_16x16x32_bf16 v[130:133], v[94:97], v[50:53], v[90:93]
	s_waitcnt lgkmcnt(5)
	v_mfma_f32_16x16x32_bf16 v[90:93], v[98:101], v[38:41], v[10:13]
	v_mfma_f32_16x16x32_bf16 v[94:97], v[98:101], v[46:49], v[14:17]
	s_waitcnt lgkmcnt(4)
	v_mfma_f32_16x16x32_bf16 v[146:149], v[102:105], v[42:45], v[90:93]
	v_mfma_f32_16x16x32_bf16 v[190:193], v[102:105], v[50:53], v[94:97]
	s_waitcnt lgkmcnt(3)
	v_mfma_f32_16x16x32_bf16 v[90:93], v[106:109], v[38:41], v[10:13]
	v_mfma_f32_16x16x32_bf16 v[94:97], v[106:109], v[46:49], v[14:17]
	s_waitcnt lgkmcnt(1)
	v_mfma_f32_16x16x32_bf16 v[10:13], v[114:117], v[38:41], v[10:13]
	v_mfma_f32_16x16x32_bf16 v[14:17], v[114:117], v[46:49], v[14:17]
	v_mfma_f32_16x16x32_bf16 v[194:197], v[110:113], v[42:45], v[90:93]
	v_mfma_f32_16x16x32_bf16 v[122:125], v[110:113], v[50:53], v[94:97]
	s_waitcnt lgkmcnt(0)
	v_mfma_f32_16x16x32_bf16 v[140:143], v[118:121], v[42:45], v[10:13]
	v_mfma_f32_16x16x32_bf16 v[136:139], v[118:121], v[50:53], v[14:17]
	ds_read_b64_tr_b16 v[94:95], v187 offset:8192
	s_nop 0
	ds_read_b64_tr_b16 v[10:11], v187 offset:8224
	ds_read_b64_tr_b16 v[96:97], v187 offset:10752
	ds_read_b64_tr_b16 v[90:91], v187 offset:13312
	ds_read_b64_tr_b16 v[92:93], v187 offset:15872
	ds_read_b64_tr_b16 v[12:13], v187 offset:10784
	ds_read_b64_tr_b16 v[14:15], v187 offset:13344
	ds_read_b64_tr_b16 v[16:17], v187 offset:15904
	ds_read_b64_tr_b16 v[102:103], v187 offset:8256
	ds_read_b64_tr_b16 v[104:105], v187 offset:10816
	ds_read_b64_tr_b16 v[98:99], v187 offset:13376
	ds_read_b64_tr_b16 v[100:101], v187 offset:15936
	ds_read_b64_tr_b16 v[106:107], v187 offset:8288
	ds_read_b64_tr_b16 v[108:109], v187 offset:10848
	ds_read_b64_tr_b16 v[110:111], v187 offset:13408
	ds_read_b64_tr_b16 v[112:113], v187 offset:15968
	ds_read_b128 v[216:219], v188 offset:18432
	ds_read_b128 v[220:223], v188 offset:18496
	ds_read_b128 v[224:227], v188 offset:18560
	ds_read_b128 v[228:231], v188 offset:18624
	s_waitcnt lgkmcnt(0)
	s_cselect_b32 s99, 1, 0
	s_bitcmp1_b32 s41, 8
	s_cbranch_scc1 .Lfx_h0p1_end
	s_cmp_ge_u32 s24, s20
	s_cbranch_scc1 .Lfx_h0p1_bar
	s_waitcnt vmcnt(5)
	ds_write_b128 v182, v[62:65] offset:18688
	s_waitcnt vmcnt(4)
	ds_write_b128 v183, v[66:69] offset:26880
	s_and_saveexec_b64 s[100:101], s[4:5]
	s_cbranch_execz .Lfx_h0p1_w
	s_waitcnt vmcnt(3)
	ds_write_b32 v184, v185 offset:37120

; #define LAS __attribute__((address_space(3)))
; template <int TY> __device__ __forceinline__ void attn_unit(LAS unsigned char* lds, const AttnArgs& a, int b, int h, int qt, int wave_s) {
;     ...
;         { const int Jn = J + 2 <= J1 ? J + 2 : J1; if (hf == 0) ATT_LOAD(A, Jn); else ATT_LOAD(B, Jn); }
;         const bool skip = (64 * J > ewhi) || (TY == 0 && 64 * J + 63 + 127 < ewlo);
;         if (!skip) {
;         int lim[2]; f32x4 cinit[2];
; #pragma unroll
;         for (int qb = 0; qb < 2; ++qb) {
;             lim[qb] = eq[qb] - 64 * J - 4 * fq;
;             const float c0 = TY == 0 ? -(mrun[qb] + slope2 * (float)lim[qb]) : -mrun[qb];
;             cinit[qb] = (f32x4){c0, c0, c0, c0};
;         }
;         f32x4 s[2][4];
;         bf16x8 kfr[4][NDS];
; #pragma unroll
;         for (int kb = 0; kb < 4; ++kb)
; #pragma unroll
;             for (int ds = 0; ds < NDS; ++ds) kfr[kb][ds] = *(const LAS bf16x8*)(sb + koff + (kb * NDS + ds) * 1024);
; #pragma unroll
;         for (int kb = 0; kb < 4; ++kb) {
; #pragma unroll
;             for (int ds = 0; ds < NDS; ++ds) {
;                 s[0][kb] = __builtin_amdgcn_mfma_f32_16x16x32_bf16(kfr[kb][ds], qf[0][ds], ds == 0 ? cinit[0] : s[0][kb], 0, 0, 0);
;                 s[1][kb] = __builtin_amdgcn_mfma_f32_16x16x32_bf16(kfr[kb][ds], qf[1][ds], ds == 0 ? cinit[1] : s[1][kb], 0, 0, 0);
;             }
;         }
;         bf16x8 vf[4][2];
; #pragma unroll
;         for (int db = 0; db < 4; ++db)
; #pragma unroll
;             for (int G = 0; G < 2; ++G) {
;                 LAS unsigned char* vp = sb + voff + (32 * G * VSTR + 16 * db) * 2;
;                 const v4i16_t lo = __builtin_amdgcn_ds_read_tr16_b64_v4i16((LAS v4i16_t*)vp), hi = __builtin_amdgcn_ds_read_tr16_b64_v4i16((LAS v4i16_t*)(vp + 16 * VSTR * 2));
;                 vf[db][G] = (bf16x8){lo[0], lo[1], lo[2], lo[3], hi[0], hi[1], hi[2], hi[3]};
;             }
;         if (TY == 1) {
; #pragma unroll
;             for (int kb = 0; kb < 4; ++kb) {
;                 const f32x4 fk = *(const LAS f32x4*)(sb + KBYTES + VBYTES + (16 * kb + 4 * fq) * 4);
;                 s[0][kb] -= fk; s[1][kb] -= fk;
;             }
;         }
.LBB0_777:
	s_andn2_b64 vcc, exec, s[8:9]
	s_cbranch_vccnz .LBB0_762
	s_cmp_ge_u32 s24, s20
	s_cbranch_scc1 .LBB0_762
	ds_read_b128 v[90:93], v186 offset:18688
	ds_read_b128 v[94:97], v186 offset:19712
	ds_read_b128 v[98:101], v186 offset:20736
	ds_read_b128 v[102:105], v186 offset:21760
	ds_read_b128 v[106:109], v186 offset:22784
	ds_read_b128 v[110:113], v186 offset:23808
	ds_read_b128 v[114:117], v186 offset:24832
	ds_read_b128 v[118:121], v186 offset:25856
	s_min_i32 s8, s22, s20
	s_lshl_b32 s10, s8, 6
	v_add_u32_e32 v1, s10, v169
	v_max_i32_e32 v11, 48, v1
	v_add_u32_e32 v10, s19, v1
	v_add_u32_e32 v11, s18, v11
	v_cmp_lt_i32_e32 vcc, 63, v1
	s_nop 1
	v_cndmask_b32_e32 v1, v11, v10, vcc
	v_mad_i64_i32 v[10:11], s[8:9], v1, s40, v[162:163]
	v_mad_i64_i32 v[12:13], s[8:9], v1, s40, v[164:165]
	global_load_dwordx4 v[62:65], v[10:11], off
	global_load_dwordx4 v[66:69], v[12:13], off
	v_add_u32_e32 v10, s10, v144
	v_ashrrev_i32_e32 v11, 31, v10
	v_lshlrev_b64 v[10:11], 5, v[10:11]
	v_lshl_add_u64 v[10:11], s[6:7], 0, v[10:11]
	global_load_dword v185, v[10:11], off
	s_sub_i32 s8, s23, 63
	s_cmp_gt_i32 s8, s21
	s_cbranch_scc1 .LBB0_787
	v_xor_b32_e32 v10, 0x80000000, v167
	v_xor_b32_e32 v14, 0x80000000, v166
	v_mov_b32_e32 v11, v10
	v_mov_b32_e32 v12, v10
	v_mov_b32_e32 v13, v10
	v_mov_b32_e32 v15, v14
	v_mov_b32_e32 v16, v14
	v_mov_b32_e32 v17, v14
	s_waitcnt lgkmcnt(7)
	v_mfma_f32_16x16x32_bf16 v[122:125], v[90:93], v[38:41], v[10:13]
	s_cmp_gt_i32 s23, s17
	s_mov_b64 s[8:9], -1
	v_mfma_f32_16x16x32_bf16 v[90:93], v[90:93], v[46:49], v[14:17]
	s_waitcnt lgkmcnt(6)
	v_mfma_f32_16x16x32_bf16 v[126:129], v[94:97], v[42:45], v[122:125]
	v_mfma_f32_16x16x32_bf16 v[130:133], v[94:97], v[50:53], v[90:93]
	s_waitcnt lgkmcnt(5)
	v_mfma_f32_16x16x32_bf16 v[90:93], v[98:101], v[38:41], v[10:13]
	v_mfma_f32_16x16x32_bf16 v[94:97], v[98:101], v[46:49], v[14:17]
	s_waitcnt lgkmcnt(4)
	v_mfma_f32_16x16x32_bf16 v[146:149], v[102:105], v[42:45], v[90:93]
	v_mfma_f32_16x16x32_bf16 v[190:193], v[102:105], v[50:53], v[94:97]
	s_waitcnt lgkmcnt(3)
	v_mfma_f32_16x16x32_bf16 v[90:93], v[106:109], v[38:41], v[10:13]
	v_mfma_f32_16x16x32_bf16 v[94:97], v[106:109], v[46:49], v[14:17]
	s_waitcnt lgkmcnt(1)
	v_mfma_f32_16x16x32_bf16 v[10:13], v[114:117], v[38:41], v[10:13]
	v_mfma_f32_16x16x32_bf16 v[14:17], v[114:117], v[46:49], v[14:17]
	v_mfma_f32_16x16x32_bf16 v[194:197], v[110:113], v[42:45], v[90:93]
	v_mfma_f32_16x16x32_bf16 v[122:125], v[110:113], v[50:53], v[94:97]
	s_waitcnt lgkmcnt(0)
	v_mfma_f32_16x16x32_bf16 v[140:143], v[118:121], v[42:45], v[10:13]
	v_mfma_f32_16x16x32_bf16 v[136:139], v[118:121], v[50:53], v[14:17]
	ds_read_b64_tr_b16 v[94:95], v187 offset:26880
	s_nop 0
	ds_read_b64_tr_b16 v[10:11], v187 offset:26912
	ds_read_b64_tr_b16 v[96:97], v187 offset:29440
	ds_read_b64_tr_b16 v[90:91], v187 offset:32000
	ds_read_b64_tr_b16 v[92:93], v187 offset:34560
	ds_read_b64_tr_b16 v[12:13], v187 offset:29472
	ds_read_b64_tr_b16 v[14:15], v187 offset:32032
	ds_read_b64_tr_b16 v[16:17], v187 offset:34592
	ds_read_b64_tr_b16 v[102:103], v187 offset:26944
	ds_read_b64_tr_b16 v[104:105], v187 offset:29504
	ds_read_b64_tr_b16 v[98:99], v187 offset:32064
	ds_read_b64_tr_b16 v[100:101], v187 offset:34624
	ds_read_b64_tr_b16 v[106:107], v187 offset:26976
	ds_read_b64_tr_b16 v[108:109], v187 offset:29536
	ds_read_b64_tr_b16 v[110:111], v187 offset:32096
	ds_read_b64_tr_b16 v[112:113], v187 offset:34656
	ds_read_b128 v[216:219], v188 offset:37120
	ds_read_b128 v[220:223], v188 offset:37184
	ds_read_b128 v[224:227], v188 offset:37248
	ds_read_b128 v[228:231], v188 offset:37312
	s_waitcnt lgkmcnt(0)
	s_cselect_b32 s99, 1, 0
	s_bitcmp1_b32 s41, 8
	s_cbranch_scc1 .Lfx_h1p1_end
	s_add_i32 s100, s22, -2
	s_cmp_ge_u32 s100, s20
	s_cbranch_scc1 .Lfx_h1p1_bar
	s_waitcnt vmcnt(5)
	ds_write_b128 v182, v[70:73]
	s_waitcnt vmcnt(4)
	ds_write_b128 v183, v[74:77] offset:8192
	s_and_saveexec_b64 s[100:101], s[4:5]
	s_cbranch_execz .Lfx_h1p1_w
	s_waitcnt vmcnt(3)
	ds_write_b32 v184, v189 offset:18432
